# norm-item H stores write-through (sc1): whole-line 512 B per wave store, so the P0 barrier has no dirty L2 backlog to flush; on top of v60
# speedup vs baseline: 1.0117x; 1.0059x over previous
.Lnorm_lat:
	s_add_u32 s68, s60, 0x1000
	s_addc_u32 s69, s61, 0
	global_load_dwordx4 v[2:5], v66, s[56:57]
	global_load_dwordx4 v[6:9], v66, s[56:57] offset:1024
	global_load_dwordx4 v[10:13], v66, s[56:57] offset:2048
	global_load_dwordx4 v[14:17], v66, s[56:57] offset:3072
	global_load_dwordx4 v[18:21], v66, s[68:69]
	global_load_dwordx4 v[22:25], v66, s[68:69] offset:1024
	global_load_dwordx4 v[26:29], v66, s[68:69] offset:2048
	global_load_dwordx4 v[30:33], v66, s[68:69] offset:3072
	global_load_dwordx4 v[34:37], v66, s[60:61]
	global_load_dwordx4 v[38:41], v66, s[60:61] offset:1024
	global_load_dwordx4 v[42:45], v66, s[60:61] offset:2048
	global_load_dwordx4 v[46:49], v66, s[60:61] offset:3072
	global_load_dwordx4 v[106:109], v66, s[62:63] nt
	global_load_dwordx4 v[110:113], v66, s[62:63] offset:1024 nt
	global_load_dwordx4 v[114:117], v66, s[62:63] offset:2048 nt
	global_load_dwordx4 v[118:121], v66, s[62:63] offset:3072 nt
	s_add_u32 s62, s62, 0x1000
	s_addc_u32 s63, s63, 0
	global_load_dwordx4 v[122:125], v66, s[62:63] nt
	global_load_dwordx4 v[126:129], v66, s[62:63] offset:1024 nt
	global_load_dwordx4 v[130:133], v66, s[62:63] offset:2048 nt
	global_load_dwordx4 v[134:137], v66, s[62:63] offset:3072 nt
	s_add_u32 s62, s62, 0x1000
	s_addc_u32 s63, s63, 0
	global_load_dwordx4 v[138:141], v66, s[62:63] nt
	global_load_dwordx4 v[142:145], v66, s[62:63] offset:1024 nt
	global_load_dwordx4 v[146:149], v66, s[62:63] offset:2048 nt
	global_load_dwordx4 v[150:153], v66, s[62:63] offset:3072 nt
	s_add_u32 s62, s62, 0x1000
	s_addc_u32 s63, s63, 0
	global_load_dwordx4 v[154:157], v66, s[62:63] nt
	global_load_dwordx4 v[158:161], v66, s[62:63] offset:1024 nt
	global_load_dwordx4 v[162:165], v66, s[62:63] offset:2048 nt
	global_load_dwordx4 v[166:169], v66, s[62:63] offset:3072 nt
	s_waitcnt vmcnt(20)
	v_pk_add_f32 v[18:19], v[18:19], 1.0 op_sel_hi:[1,0]
	v_pk_add_f32 v[20:21], v[20:21], 1.0 op_sel_hi:[1,0]
	v_pk_add_f32 v[22:23], v[22:23], 1.0 op_sel_hi:[1,0]
	v_pk_add_f32 v[24:25], v[24:25], 1.0 op_sel_hi:[1,0]
	v_pk_add_f32 v[26:27], v[26:27], 1.0 op_sel_hi:[1,0]
	v_pk_add_f32 v[28:29], v[28:29], 1.0 op_sel_hi:[1,0]
	v_pk_add_f32 v[30:31], v[30:31], 1.0 op_sel_hi:[1,0]
	v_pk_add_f32 v[32:33], v[32:33], 1.0 op_sel_hi:[1,0]
	v_pk_mul_f32 v[2:3], v[2:3], v[18:19]
	v_pk_mul_f32 v[4:5], v[4:5], v[20:21]
	v_pk_mul_f32 v[6:7], v[6:7], v[22:23]
	v_pk_mul_f32 v[8:9], v[8:9], v[24:25]
	v_pk_mul_f32 v[10:11], v[10:11], v[26:27]
	v_pk_mul_f32 v[12:13], v[12:13], v[28:29]
	v_pk_mul_f32 v[14:15], v[14:15], v[30:31]
	v_pk_mul_f32 v[16:17], v[16:17], v[32:33]
	s_waitcnt vmcnt(0)
	v_pk_mul_f32 v[86:87], v[106:107], v[106:107]
	v_pk_mul_f32 v[88:89], v[108:109], v[108:109]
	v_pk_mul_f32 v[90:91], v[122:123], v[122:123]
	v_pk_mul_f32 v[92:93], v[124:125], v[124:125]
	v_pk_mul_f32 v[94:95], v[138:139], v[138:139]
	v_pk_mul_f32 v[96:97], v[140:141], v[140:141]
	v_pk_mul_f32 v[98:99], v[154:155], v[154:155]
	v_pk_mul_f32 v[100:101], v[156:157], v[156:157]
	v_pk_fma_f32 v[86:87], v[110:111], v[110:111], v[86:87]
	v_pk_fma_f32 v[88:89], v[112:113], v[112:113], v[88:89]
	v_pk_fma_f32 v[90:91], v[126:127], v[126:127], v[90:91]
	v_pk_fma_f32 v[92:93], v[128:129], v[128:129], v[92:93]
	v_pk_fma_f32 v[94:95], v[142:143], v[142:143], v[94:95]
	v_pk_fma_f32 v[96:97], v[144:145], v[144:145], v[96:97]
	v_pk_fma_f32 v[98:99], v[158:159], v[158:159], v[98:99]
	v_pk_fma_f32 v[100:101], v[160:161], v[160:161], v[100:101]
	v_pk_fma_f32 v[86:87], v[114:115], v[114:115], v[86:87]
	v_pk_fma_f32 v[88:89], v[116:117], v[116:117], v[88:89]
	v_pk_fma_f32 v[90:91], v[130:131], v[130:131], v[90:91]
	v_pk_fma_f32 v[92:93], v[132:133], v[132:133], v[92:93]
	v_pk_fma_f32 v[94:95], v[146:147], v[146:147], v[94:95]
	v_pk_fma_f32 v[96:97], v[148:149], v[148:149], v[96:97]
	v_pk_fma_f32 v[98:99], v[162:163], v[162:163], v[98:99]
	v_pk_fma_f32 v[100:101], v[164:165], v[164:165], v[100:101]
	v_pk_fma_f32 v[86:87], v[118:119], v[118:119], v[86:87]
	v_pk_fma_f32 v[88:89], v[120:121], v[120:121], v[88:89]
	v_pk_fma_f32 v[90:91], v[134:135], v[134:135], v[90:91]
	v_pk_fma_f32 v[92:93], v[136:137], v[136:137], v[92:93]
	v_pk_fma_f32 v[94:95], v[150:151], v[150:151], v[94:95]
	v_pk_fma_f32 v[96:97], v[152:153], v[152:153], v[96:97]
	v_pk_fma_f32 v[98:99], v[166:167], v[166:167], v[98:99]
	v_pk_fma_f32 v[100:101], v[168:169], v[168:169], v[100:101]
	v_pk_add_f32 v[86:87], v[86:87], v[88:89]
	v_pk_add_f32 v[90:91], v[90:91], v[92:93]
	v_pk_add_f32 v[94:95], v[94:95], v[96:97]
	v_pk_add_f32 v[98:99], v[98:99], v[100:101]
	v_add_f32_e32 v50, v86, v87
	v_add_f32_e32 v51, v90, v91
	v_add_f32_e32 v52, v94, v95
	v_add_f32_e32 v53, v98, v99
	v_add_f32_dpp v50, v50, v50 quad_perm:[1,0,3,2] row_mask:0xf bank_mask:0xf
	v_add_f32_dpp v51, v51, v51 quad_perm:[1,0,3,2] row_mask:0xf bank_mask:0xf
	v_add_f32_dpp v52, v52, v52 quad_perm:[1,0,3,2] row_mask:0xf bank_mask:0xf
	v_add_f32_dpp v53, v53, v53 quad_perm:[1,0,3,2] row_mask:0xf bank_mask:0xf
	v_add_f32_dpp v50, v50, v50 quad_perm:[2,3,0,1] row_mask:0xf bank_mask:0xf
	v_add_f32_dpp v51, v51, v51 quad_perm:[2,3,0,1] row_mask:0xf bank_mask:0xf
	v_add_f32_dpp v52, v52, v52 quad_perm:[2,3,0,1] row_mask:0xf bank_mask:0xf
	v_add_f32_dpp v53, v53, v53 quad_perm:[2,3,0,1] row_mask:0xf bank_mask:0xf
	v_add_f32_dpp v50, v50, v50 row_half_mirror row_mask:0xf bank_mask:0xf
	v_add_f32_dpp v51, v51, v51 row_half_mirror row_mask:0xf bank_mask:0xf
	v_add_f32_dpp v52, v52, v52 row_half_mirror row_mask:0xf bank_mask:0xf
	v_add_f32_dpp v53, v53, v53 row_half_mirror row_mask:0xf bank_mask:0xf
	v_add_f32_dpp v50, v50, v50 row_mirror row_mask:0xf bank_mask:0xf
	v_add_f32_dpp v51, v51, v51 row_mirror row_mask:0xf bank_mask:0xf
	v_add_f32_dpp v52, v52, v52 row_mirror row_mask:0xf bank_mask:0xf
	v_add_f32_dpp v53, v53, v53 row_mirror row_mask:0xf bank_mask:0xf
	v_add_f32_dpp v50, v50, v50 row_bcast:15 row_mask:0xa bank_mask:0xf
	v_add_f32_dpp v51, v51, v51 row_bcast:15 row_mask:0xa bank_mask:0xf
	v_add_f32_dpp v52, v52, v52 row_bcast:15 row_mask:0xa bank_mask:0xf
	v_add_f32_dpp v53, v53, v53 row_bcast:15 row_mask:0xa bank_mask:0xf
	v_add_f32_dpp v50, v50, v50 row_bcast:31 row_mask:0xc bank_mask:0xf
	v_add_f32_dpp v51, v51, v51 row_bcast:31 row_mask:0xc bank_mask:0xf
	v_add_f32_dpp v52, v52, v52 row_bcast:31 row_mask:0xc bank_mask:0xf
	v_add_f32_dpp v53, v53, v53 row_bcast:31 row_mask:0xc bank_mask:0xf
	v_readlane_b32 s52, v50, 63
	v_readlane_b32 s53, v51, 63
	v_readlane_b32 s54, v52, 63
	v_readlane_b32 s55, v53, 63
	v_mov_b32_e32 v60, s52
	v_mov_b32_e32 v62, s53
	v_mov_b32_e32 v64, s54
	v_mov_b32_e32 v84, s55
	v_fmamk_f32 v60, v60, 0x3a800000, v68
	v_fmamk_f32 v62, v62, 0x3a800000, v68
	v_fmamk_f32 v64, v64, 0x3a800000, v68
	v_fmamk_f32 v84, v84, 0x3a800000, v68
	v_rsq_f32_e32 v60, v60
	v_rsq_f32_e32 v62, v62
	v_rsq_f32_e32 v64, v64
	v_rsq_f32_e32 v84, v84
	v_pk_mul_f32 v[106:107], v[60:61], v[106:107] op_sel_hi:[0,1]
	v_pk_mul_f32 v[108:109], v[60:61], v[108:109] op_sel_hi:[0,1]
	v_pk_mul_f32 v[110:111], v[60:61], v[110:111] op_sel_hi:[0,1]
	v_pk_mul_f32 v[112:113], v[60:61], v[112:113] op_sel_hi:[0,1]
	v_pk_mul_f32 v[114:115], v[60:61], v[114:115] op_sel_hi:[0,1]
	v_pk_mul_f32 v[116:117], v[60:61], v[116:117] op_sel_hi:[0,1]
	v_pk_mul_f32 v[118:119], v[60:61], v[118:119] op_sel_hi:[0,1]
	v_pk_mul_f32 v[120:121], v[60:61], v[120:121] op_sel_hi:[0,1]
	v_pk_fma_f32 v[106:107], v[106:107], v[2:3], v[34:35]
	v_pk_fma_f32 v[108:109], v[108:109], v[4:5], v[36:37]
	v_pk_fma_f32 v[110:111], v[110:111], v[6:7], v[38:39]
	v_pk_fma_f32 v[112:113], v[112:113], v[8:9], v[40:41]
	v_pk_fma_f32 v[114:115], v[114:115], v[10:11], v[42:43]
	v_pk_fma_f32 v[116:117], v[116:117], v[12:13], v[44:45]
	v_pk_fma_f32 v[118:119], v[118:119], v[14:15], v[46:47]
	v_pk_fma_f32 v[120:121], v[120:121], v[16:17], v[48:49]
	v_cvt_pk_bf16_f32 v106, v106, v107
	v_cvt_pk_bf16_f32 v107, v108, v109
	v_cvt_pk_bf16_f32 v110, v110, v111
	v_cvt_pk_bf16_f32 v111, v112, v113
	v_cvt_pk_bf16_f32 v114, v114, v115
	v_cvt_pk_bf16_f32 v115, v116, v117
	v_cvt_pk_bf16_f32 v118, v118, v119
	v_cvt_pk_bf16_f32 v119, v120, v121
	global_store_dwordx2 v82, v[106:107], s[64:65] sc1
	global_store_dwordx2 v82, v[110:111], s[64:65] offset:512 sc1
	global_store_dwordx2 v82, v[114:115], s[64:65] offset:1024 sc1
	global_store_dwordx2 v82, v[118:119], s[64:65] offset:1536 sc1
	s_add_u32 s64, s64, 0x800
	s_addc_u32 s65, s65, 0
	v_pk_mul_f32 v[122:123], v[62:63], v[122:123] op_sel_hi:[0,1]
	v_pk_mul_f32 v[124:125], v[62:63], v[124:125] op_sel_hi:[0,1]
	v_pk_mul_f32 v[126:127], v[62:63], v[126:127] op_sel_hi:[0,1]
	v_pk_mul_f32 v[128:129], v[62:63], v[128:129] op_sel_hi:[0,1]
	v_pk_mul_f32 v[130:131], v[62:63], v[130:131] op_sel_hi:[0,1]
	v_pk_mul_f32 v[132:133], v[62:63], v[132:133] op_sel_hi:[0,1]
	v_pk_mul_f32 v[134:135], v[62:63], v[134:135] op_sel_hi:[0,1]
	v_pk_mul_f32 v[136:137], v[62:63], v[136:137] op_sel_hi:[0,1]
	v_pk_fma_f32 v[122:123], v[122:123], v[2:3], v[34:35]
	v_pk_fma_f32 v[124:125], v[124:125], v[4:5], v[36:37]
	v_pk_fma_f32 v[126:127], v[126:127], v[6:7], v[38:39]
	v_pk_fma_f32 v[128:129], v[128:129], v[8:9], v[40:41]
	v_pk_fma_f32 v[130:131], v[130:131], v[10:11], v[42:43]
	v_pk_fma_f32 v[132:133], v[132:133], v[12:13], v[44:45]
	v_pk_fma_f32 v[134:135], v[134:135], v[14:15], v[46:47]
	v_pk_fma_f32 v[136:137], v[136:137], v[16:17], v[48:49]
	v_cvt_pk_bf16_f32 v122, v122, v123
	v_cvt_pk_bf16_f32 v123, v124, v125
	v_cvt_pk_bf16_f32 v126, v126, v127
	v_cvt_pk_bf16_f32 v127, v128, v129
	v_cvt_pk_bf16_f32 v130, v130, v131
	v_cvt_pk_bf16_f32 v131, v132, v133
	v_cvt_pk_bf16_f32 v134, v134, v135
	v_cvt_pk_bf16_f32 v135, v136, v137
	global_store_dwordx2 v82, v[122:123], s[64:65] sc1
	global_store_dwordx2 v82, v[126:127], s[64:65] offset:512 sc1
	global_store_dwordx2 v82, v[130:131], s[64:65] offset:1024 sc1
	global_store_dwordx2 v82, v[134:135], s[64:65] offset:1536 sc1
	s_add_u32 s64, s64, 0x800
	s_addc_u32 s65, s65, 0
	v_pk_mul_f32 v[138:139], v[64:65], v[138:139] op_sel_hi:[0,1]
	v_pk_mul_f32 v[140:141], v[64:65], v[140:141] op_sel_hi:[0,1]
	v_pk_mul_f32 v[142:143], v[64:65], v[142:143] op_sel_hi:[0,1]
	v_pk_mul_f32 v[144:145], v[64:65], v[144:145] op_sel_hi:[0,1]
	v_pk_mul_f32 v[146:147], v[64:65], v[146:147] op_sel_hi:[0,1]
	v_pk_mul_f32 v[148:149], v[64:65], v[148:149] op_sel_hi:[0,1]
	v_pk_mul_f32 v[150:151], v[64:65], v[150:151] op_sel_hi:[0,1]
	v_pk_mul_f32 v[152:153], v[64:65], v[152:153] op_sel_hi:[0,1]
	v_pk_fma_f32 v[138:139], v[138:139], v[2:3], v[34:35]
	v_pk_fma_f32 v[140:141], v[140:141], v[4:5], v[36:37]
	v_pk_fma_f32 v[142:143], v[142:143], v[6:7], v[38:39]
	v_pk_fma_f32 v[144:145], v[144:145], v[8:9], v[40:41]
	v_pk_fma_f32 v[146:147], v[146:147], v[10:11], v[42:43]
	v_pk_fma_f32 v[148:149], v[148:149], v[12:13], v[44:45]
	v_pk_fma_f32 v[150:151], v[150:151], v[14:15], v[46:47]
	v_pk_fma_f32 v[152:153], v[152:153], v[16:17], v[48:49]
	v_cvt_pk_bf16_f32 v138, v138, v139
	v_cvt_pk_bf16_f32 v139, v140, v141
	v_cvt_pk_bf16_f32 v142, v142, v143
	v_cvt_pk_bf16_f32 v143, v144, v145
	v_cvt_pk_bf16_f32 v146, v146, v147
	v_cvt_pk_bf16_f32 v147, v148, v149
	v_cvt_pk_bf16_f32 v150, v150, v151
	v_cvt_pk_bf16_f32 v151, v152, v153
	global_store_dwordx2 v82, v[138:139], s[64:65] sc1
	global_store_dwordx2 v82, v[142:143], s[64:65] offset:512 sc1
	global_store_dwordx2 v82, v[146:147], s[64:65] offset:1024 sc1
	global_store_dwordx2 v82, v[150:151], s[64:65] offset:1536 sc1
	s_add_u32 s64, s64, 0x800
	s_addc_u32 s65, s65, 0
	v_pk_mul_f32 v[154:155], v[84:85], v[154:155] op_sel_hi:[0,1]
	v_pk_mul_f32 v[156:157], v[84:85], v[156:157] op_sel_hi:[0,1]
	v_pk_mul_f32 v[158:159], v[84:85], v[158:159] op_sel_hi:[0,1]
	v_pk_mul_f32 v[160:161], v[84:85], v[160:161] op_sel_hi:[0,1]
	v_pk_mul_f32 v[162:163], v[84:85], v[162:163] op_sel_hi:[0,1]
	v_pk_mul_f32 v[164:165], v[84:85], v[164:165] op_sel_hi:[0,1]
	v_pk_mul_f32 v[166:167], v[84:85], v[166:167] op_sel_hi:[0,1]
	v_pk_mul_f32 v[168:169], v[84:85], v[168:169] op_sel_hi:[0,1]
	v_pk_fma_f32 v[154:155], v[154:155], v[2:3], v[34:35]
	v_pk_fma_f32 v[156:157], v[156:157], v[4:5], v[36:37]
	v_pk_fma_f32 v[158:159], v[158:159], v[6:7], v[38:39]
	v_pk_fma_f32 v[160:161], v[160:161], v[8:9], v[40:41]
	v_pk_fma_f32 v[162:163], v[162:163], v[10:11], v[42:43]
	v_pk_fma_f32 v[164:165], v[164:165], v[12:13], v[44:45]
	v_pk_fma_f32 v[166:167], v[166:167], v[14:15], v[46:47]
	v_pk_fma_f32 v[168:169], v[168:169], v[16:17], v[48:49]
	v_cvt_pk_bf16_f32 v154, v154, v155
	v_cvt_pk_bf16_f32 v155, v156, v157
	v_cvt_pk_bf16_f32 v158, v158, v159
	v_cvt_pk_bf16_f32 v159, v160, v161
	v_cvt_pk_bf16_f32 v162, v162, v163
	v_cvt_pk_bf16_f32 v163, v164, v165
	v_cvt_pk_bf16_f32 v166, v166, v167
	v_cvt_pk_bf16_f32 v167, v168, v169
	global_store_dwordx2 v82, v[154:155], s[64:65] sc1
	global_store_dwordx2 v82, v[158:159], s[64:65] offset:512 sc1
	global_store_dwordx2 v82, v[162:163], s[64:65] offset:1024 sc1
	global_store_dwordx2 v82, v[166:167], s[64:65] offset:1536 sc1
	s_add_u32 s64, s64, 0x800
	s_addc_u32 s65, s65, 0
	s_mov_b32 s68, 0x2aaaaaab
	s_mov_b64 s[52:53], 0
